# v40 + gate/up epilogue: the 8 per-row sumsq loads issued together then one wait (were 8 load-wait round trips)
# speedup vs baseline: 1.0046x; 1.0046x over previous
;     DI void operator()(const AccT& acc, const Unit& u, int wr, int wc, int fr, int fq, LAS unsigned char* ldsx) const {
;     ...
;         for (int n = 0; n < 2; ++n) { const int f = u.pn * 128 + wc * 32 + 16 * n + 4 * fq;
;             w0[n] = *(const f32x4*)(convw + f); w1[n] = *(const f32x4*)(convw + DFF + f); w2[n] = *(const f32x4*)(convw + 2 * DFF + f); cb[n] = *(const f32x4*)(convb + f); }
;         float rs[2][4];
; #pragma unroll
;         for (int ai = 0; ai < 2; ++ai)
; #pragma unroll
;             for (int m = 0; m < 4; ++m) { const int tok = tok0 + 128 * ai + 16 * m; const bool ok = tok >= 0 && tok < (prompt ? SEQ : MTOK);
;                 rs[ai][m] = ok ? rsqrtf(sumsq[ok ? tok : 0] * (1.f / DM) + EPS) : 0.f; }
.LBB0_833:
	v_lshl_or_b32 v216, s28, 7, v244
	v_ashrrev_i32_e32 v217, 31, v216
	v_lshlrev_b64 v[196:197], 2, v[216:217]
	v_or_b32_e32 v182, 16, v216
	v_lshl_add_u64 v[46:47], s[10:11], 0, v[196:197]
	v_lshl_add_u64 v[48:49], s[12:13], 0, v[196:197]
	v_ashrrev_i32_e32 v183, 31, v182
	global_load_dwordx4 v[124:127], v[46:47], off
	global_load_dwordx4 v[128:131], v[48:49], off
	v_lshlrev_b64 v[48:49], 2, v[182:183]
	v_lshl_add_u64 v[44:45], s[48:49], 0, v[196:197]
	v_lshl_add_u64 v[56:57], s[50:51], 0, v[196:197]
	v_lshl_add_u64 v[50:51], s[10:11], 0, v[48:49]
	v_lshl_add_u64 v[52:53], s[12:13], 0, v[48:49]
	global_load_dwordx4 v[132:135], v[44:45], off
	s_nop 0
	global_load_dwordx4 v[44:47], v[44:45], off offset:64
	s_nop 0
	global_load_dwordx4 v[48:51], v[50:51], off
	s_nop 0
	global_load_dwordx4 v[52:55], v[52:53], off
	s_nop 0
	global_load_dwordx4 v[136:139], v[56:57], off
	s_nop 0
	global_load_dwordx4 v[56:59], v[56:57], off offset:64
	v_add_u32_e32 v172, s29, v240
	v_cmp_gt_u32_e32 vcc, s23, v172
	v_mov_b32_e32 v210, 0
	v_mov_b32_e32 v214, 0
	s_and_saveexec_b64 s[28:29], vcc
	s_cbranch_execz .LBB0_835
	v_lshl_add_u64 v[160:161], v[172:173], 2, s[58:59]
	global_load_dword v214, v[160:161], off
.LBB0_835:
	s_or_b64 exec, exec, s[28:29]
	v_add_u32_e32 v212, 16, v172
	v_cmp_gt_u32_e32 vcc, s23, v212
	s_and_saveexec_b64 s[28:29], vcc
	s_cbranch_execz .LBB0_837
	v_mov_b32_e32 v213, v173
	v_lshl_add_u64 v[160:161], v[212:213], 2, s[58:59]
	global_load_dword v210, v[160:161], off
.LBB0_837:
	s_or_b64 exec, exec, s[28:29]
	v_add_u32_e32 v206, 32, v172
	v_cmp_gt_u32_e32 vcc, s23, v206
	v_mov_b32_e32 v202, 0
	v_mov_b32_e32 v208, 0
	s_and_saveexec_b64 s[28:29], vcc
	s_cbranch_execz .LBB0_839
	v_mov_b32_e32 v207, v173
	v_lshl_add_u64 v[160:161], v[206:207], 2, s[58:59]
	global_load_dword v208, v[160:161], off
.LBB0_839:
	s_or_b64 exec, exec, s[28:29]
	v_add_u32_e32 v204, 48, v172
	v_cmp_gt_u32_e32 vcc, s23, v204
	s_and_saveexec_b64 s[28:29], vcc
	s_cbranch_execz .LBB0_841
	v_mov_b32_e32 v205, v173
	v_lshl_add_u64 v[160:161], v[204:205], 2, s[58:59]
	global_load_dword v202, v[160:161], off
.LBB0_841:
	s_or_b64 exec, exec, s[28:29]
	v_add_u32_e32 v198, 0x80, v172
	v_cmp_gt_u32_e32 vcc, s23, v198
	v_mov_b32_e32 v192, 0
	v_mov_b32_e32 v200, 0
	s_and_saveexec_b64 s[28:29], vcc
	s_cbranch_execz .LBB0_843
	v_mov_b32_e32 v199, v173
	v_lshl_add_u64 v[160:161], v[198:199], 2, s[58:59]
	global_load_dword v200, v[160:161], off
.LBB0_843:
	s_or_b64 exec, exec, s[28:29]
	v_add_u32_e32 v194, 0x90, v172
	v_cmp_gt_u32_e32 vcc, s23, v194
	s_and_saveexec_b64 s[28:29], vcc
	s_cbranch_execz .LBB0_845
	v_mov_b32_e32 v195, v173
	v_lshl_add_u64 v[160:161], v[194:195], 2, s[58:59]
	global_load_dword v192, v[160:161], off
.LBB0_845:
	s_or_b64 exec, exec, s[28:29]
	v_add_u32_e32 v188, 0xa0, v172
	v_cmp_gt_u32_e32 vcc, s23, v188
	v_mov_b32_e32 v184, 0
	v_mov_b32_e32 v190, 0
	s_and_saveexec_b64 s[28:29], vcc
	s_cbranch_execz .LBB0_847
	v_mov_b32_e32 v189, v173
	v_lshl_add_u64 v[160:161], v[188:189], 2, s[58:59]
	global_load_dword v190, v[160:161], off
.LBB0_847:
	s_or_b64 exec, exec, s[28:29]
	v_add_u32_e32 v186, 0xb0, v172
	v_cmp_gt_u32_e32 vcc, s23, v186
	s_and_saveexec_b64 s[28:29], vcc
	s_cbranch_execz .LBB0_849
	v_mov_b32_e32 v187, v173
	v_lshl_add_u64 v[160:161], v[186:187], 2, s[58:59]
	global_load_dword v184, v[160:161], off
.LBB0_849:
	s_or_b64 exec, exec, s[28:29]
	s_waitcnt vmcnt(0)
	s_mov_b32 s30, 0x800000
	v_cmp_gt_u32_e32 vcc, s23, v172
	s_and_saveexec_b64 s[28:29], vcc
	s_cbranch_execz .Lrs_skip0
	v_fmamk_f32 v160, v214, 0x3a800000, v236
	v_mul_f32_e32 v161, 0x4b800000, v160
	v_cmp_gt_f32_e32 vcc, s30, v160
	s_nop 1
	v_cndmask_b32_e32 v160, v160, v161, vcc
	v_rsq_f32_e32 v160, v160
	s_nop 0
	v_mul_f32_e32 v161, 0x45800000, v160
	v_cndmask_b32_e32 v214, v160, v161, vcc
; #define LAS __attribute__((address_space(3)))
;     DI void operator()(const AccT& acc, const Unit& u, int wr, int wc, int fr, int fq, LAS unsigned char* ldsx) const {
;     ...
;             for (int m = 0; m < 4; ++m) { const int tok = tok0 + 128 * ai + 16 * m; const bool ok = tok >= 0 && tok < (prompt ? SEQ : MTOK);
;                 rs[ai][m] = ok ? rsqrtf(sumsq[ok ? tok : 0] * (1.f / DM) + EPS) : 0.f; }
;         if (prompt) {
;             if (fr >= 14) {
; #pragma unroll
;                 for (int ai = 0; ai < 2; ++ai)
; #pragma unroll
;                     for (int n = 0; n < 2; ++n) *(LAS f32x4*)(H + ((ai * 2 + wr) * 4 + wc) * 64 + (fr - 14) * 32 + 16 * n + 4 * fq) = acc[ai][0][3][n] * rs[ai][3];
;             }
.Lrs_skip0:
	s_or_b64 exec, exec, s[28:29]
	v_cmp_gt_u32_e32 vcc, s23, v212
	s_and_saveexec_b64 s[28:29], vcc
	s_cbranch_execz .Lrs_skip1
	v_fmamk_f32 v160, v210, 0x3a800000, v236
	v_mul_f32_e32 v161, 0x4b800000, v160
	v_cmp_gt_f32_e32 vcc, s30, v160
	s_nop 1
	v_cndmask_b32_e32 v160, v160, v161, vcc
	v_rsq_f32_e32 v160, v160
	s_nop 0
	v_mul_f32_e32 v161, 0x45800000, v160
	v_cndmask_b32_e32 v210, v160, v161, vcc
.Lrs_skip1:
	s_or_b64 exec, exec, s[28:29]
	v_cmp_gt_u32_e32 vcc, s23, v206
	s_and_saveexec_b64 s[28:29], vcc
	s_cbranch_execz .Lrs_skip2
	v_fmamk_f32 v160, v208, 0x3a800000, v236
	v_mul_f32_e32 v161, 0x4b800000, v160
	v_cmp_gt_f32_e32 vcc, s30, v160
	s_nop 1
	v_cndmask_b32_e32 v160, v160, v161, vcc
	v_rsq_f32_e32 v160, v160
	s_nop 0
	v_mul_f32_e32 v161, 0x45800000, v160
	v_cndmask_b32_e32 v208, v160, v161, vcc
.Lrs_skip2:
	s_or_b64 exec, exec, s[28:29]
	v_cmp_gt_u32_e32 vcc, s23, v204
	s_and_saveexec_b64 s[28:29], vcc
	s_cbranch_execz .Lrs_skip3
	v_fmamk_f32 v160, v202, 0x3a800000, v236
	v_mul_f32_e32 v161, 0x4b800000, v160
	v_cmp_gt_f32_e32 vcc, s30, v160
	s_nop 1
	v_cndmask_b32_e32 v160, v160, v161, vcc
	v_rsq_f32_e32 v160, v160
	s_nop 0
	v_mul_f32_e32 v161, 0x45800000, v160
	v_cndmask_b32_e32 v202, v160, v161, vcc
.Lrs_skip3:
	s_or_b64 exec, exec, s[28:29]
	v_cmp_gt_u32_e32 vcc, s23, v198
	s_and_saveexec_b64 s[28:29], vcc
	s_cbranch_execz .Lrs_skip4
	v_fmamk_f32 v160, v200, 0x3a800000, v236
	v_mul_f32_e32 v161, 0x4b800000, v160
	v_cmp_gt_f32_e32 vcc, s30, v160
	s_nop 1
	v_cndmask_b32_e32 v160, v160, v161, vcc
	v_rsq_f32_e32 v160, v160
	s_nop 0
	v_mul_f32_e32 v161, 0x45800000, v160
	v_cndmask_b32_e32 v200, v160, v161, vcc
.Lrs_skip4:
	s_or_b64 exec, exec, s[28:29]
	v_cmp_gt_u32_e32 vcc, s23, v194
	s_and_saveexec_b64 s[28:29], vcc
	s_cbranch_execz .Lrs_skip5
	v_fmamk_f32 v160, v192, 0x3a800000, v236
	v_mul_f32_e32 v161, 0x4b800000, v160
	v_cmp_gt_f32_e32 vcc, s30, v160
	s_nop 1
	v_cndmask_b32_e32 v160, v160, v161, vcc
	v_rsq_f32_e32 v160, v160
	s_nop 0
	v_mul_f32_e32 v161, 0x45800000, v160
	v_cndmask_b32_e32 v192, v160, v161, vcc
.Lrs_skip5:
	s_or_b64 exec, exec, s[28:29]
	v_cmp_gt_u32_e32 vcc, s23, v188
	s_and_saveexec_b64 s[28:29], vcc
	s_cbranch_execz .Lrs_skip6
	v_fmamk_f32 v160, v190, 0x3a800000, v236
	v_mul_f32_e32 v161, 0x4b800000, v160
	v_cmp_gt_f32_e32 vcc, s30, v160
	s_nop 1
	v_cndmask_b32_e32 v160, v160, v161, vcc
	v_rsq_f32_e32 v160, v160
	s_nop 0
	v_mul_f32_e32 v161, 0x45800000, v160
	v_cndmask_b32_e32 v190, v160, v161, vcc
.Lrs_skip6:
	s_or_b64 exec, exec, s[28:29]
	v_cmp_gt_u32_e32 vcc, s23, v186
	s_and_saveexec_b64 s[28:29], vcc
	s_cbranch_execz .Lrs_skip7
	v_fmamk_f32 v160, v184, 0x3a800000, v236
	v_mul_f32_e32 v161, 0x4b800000, v160
	v_cmp_gt_f32_e32 vcc, s30, v160
	s_nop 1
	v_cndmask_b32_e32 v160, v160, v161, vcc
	v_rsq_f32_e32 v160, v160
	s_nop 0
	v_mul_f32_e32 v161, 0x45800000, v160
	v_cndmask_b32_e32 v184, v160, v161, vcc
.Lrs_skip7:
	s_or_b64 exec, exec, s[28:29]
	s_mov_b32 s23, 0x800000
	v_cndmask_b32_e64 v160, 0, 1, s[0:1]
	v_cmp_ne_u32_e64 s[44:45], 1, v160
	s_andn2_b64 vcc, exec, s[0:1]
	s_cbranch_vccnz .LBB0_853
	s_mov_b64 s[0:1], exec
	v_readlane_b32 s28, v252, 0
	v_readlane_b32 s29, v252, 1
	s_and_b64 s[28:29], s[0:1], s[28:29]
	s_mov_b64 exec, s[28:29]
	s_cbranch_execz .LBB0_852
	v_pk_mul_f32 v[162:163], v[118:119], v[202:203] op_sel_hi:[1,0]
	v_pk_mul_f32 v[160:161], v[116:117], v[202:203] op_sel_hi:[1,0]
	ds_write_b128 v246, v[160:163]
	v_pk_mul_f32 v[162:163], v[38:39], v[202:203] op_sel_hi:[1,0]
	v_pk_mul_f32 v[160:161], v[36:37], v[202:203] op_sel_hi:[1,0]
	ds_write_b128 v246, v[160:163] offset:64
	v_pk_mul_f32 v[162:163], v[86:87], v[184:185] op_sel_hi:[1,0]
	v_pk_mul_f32 v[160:161], v[84:85], v[184:185] op_sel_hi:[1,0]
	v_add_u32_e32 v164, v242, v228
	ds_write_b128 v164, v[160:163] offset:256
	v_pk_mul_f32 v[162:163], v[6:7], v[184:185] op_sel_hi:[1,0]
	v_pk_mul_f32 v[160:161], v[4:5], v[184:185] op_sel_hi:[1,0]
	ds_write_b128 v164, v[160:163] offset:320
